# attention PV: V staged row-major with two ds_write_b128, B fragments fetched with ds_read_b64_tr_b16 (LDS transpose read) instead of 16 ds_write_b16 per thread
# baseline (speedup 1.0000x reference)
; __device__ __forceinline__ void attn_tile(const Params& p, int l, int tile, unsigned char* smem) {
;     ...
;   const int ntile = nb + 4;
;   const int lr = tid >> 3, lc = tid & 7;
;   uint4 kr0, kr1, vr0, vr1;
;     ...
;   KVLOAD(0);
;   for (int kt = 0; kt < ntile; ++kt) {
;     __syncthreads();
;     *(uint4*)(Ks + lr * 72 + lc * 8) = kr0;
;     *(uint4*)(Ks + (lr + 32) * 72 + lc * 8) = kr1;
;     VTSTORE(vr0, lr);
;     VTSTORE(vr1, lr + 32);
;     __syncthreads();
;     if (kt + 1 < ntile) KVLOAD(kt + 1);
.LBB0_523:
	s_andn2_b64 vcc, exec, s[46:47]
	s_cbranch_vccnz .LBB0_545
	s_mul_i32 s46, s49, 0x56
	s_bfe_u32 s47, s46, 0x1000f
	s_bfe_u32 s46, s46, 0x80008
	s_add_i32 s46, s46, s47
	s_sext_i32_i8 s46, s46
	s_lshl_b32 s46, s46, 6
	s_ashr_i32 s47, s46, 31
	s_add_i32 s64, s59, 4
	v_ashrrev_i32_e32 v100, 3, v4
	s_add_u32 s44, s44, s51
	v_ashrrev_i32_e32 v101, 31, v100
	s_addc_u32 s45, s45, 0
	v_lshl_add_u64 v[6:7], s[44:45], 0, v[100:101]
	v_readlane_b32 s0, v251, 48
	v_lshlrev_b32_e32 v1, 3, v4
	v_lshlrev_b64 v[6:7], 11, v[6:7]
	v_readlane_b32 s8, v251, 56
	v_readlane_b32 s9, v251, 57
	v_and_b32_e32 v1, 56, v1
	s_lshl_b64 s[44:45], s[46:47], 1
	v_lshl_add_u64 v[6:7], s[8:9], 0, v[6:7]
	v_lshlrev_b32_e32 v4, 1, v1
	v_lshl_add_u64 v[6:7], v[6:7], 0, s[44:45]
	v_mov_b32_e32 v5, v164
	v_lshl_add_u64 v[6:7], v[6:7], 0, v[4:5]
	v_add_co_u32_e32 v8, vcc, s27, v6
	s_add_u32 s46, s56, s50
	s_nop 0
	v_addc_co_u32_e32 v9, vcc, 0, v7, vcc
	global_load_dwordx4 v[52:55], v[8:9], off offset:1024
	global_load_dwordx4 v[60:63], v[8:9], off offset:768
	global_load_dwordx4 v[48:51], v[6:7], off offset:1024
	global_load_dwordx4 v[56:59], v[6:7], off offset:768
	s_addc_u32 s47, s57, 0
	s_add_u32 s65, s46, 0x100
	s_movk_i32 s0, 0x1200
	s_addc_u32 s66, s47, 0
	v_mul_lo_u32 v3, v3, s0
	v_mul_u32_u24_e32 v1, 0x48, v1
	s_add_u32 s44, s8, s44
	v_add_u32_e32 v3, 0, v3
	v_lshlrev_b32_e32 v6, 1, v100
	v_lshlrev_b32_e32 v1, 1, v1
	s_addc_u32 s45, s9, s45
	s_addk_i32 s48, 0xff4f
	v_add_u32_e32 v7, 0, v4
	s_movk_i32 s0, 0x90
	v_add3_u32 v109, 0, v6, v1
	v_add3_u32 v110, 0, v1, v6
	v_add_u32_e32 v1, 0, v0
	v_lshl_add_u32 v6, v104, 1, v3
	v_add_u32_e32 v3, v3, v0
	v_lshl_add_u64 v[102:103], s[44:45], 0, v[4:5]
	v_add3_u32 v0, s48, v98, v105
	v_add_u32_e32 v4, s50, v104
	v_mul_lo_u32 v8, v100, s0
	v_mul_u32_u24_e32 v9, 0x90, v104
	v_mul_u32_u24_e32 v2, 0x240, v2
	v_sub_u32_e32 v111, v0, v4
	v_mov_b32_e32 v0, 0
	v_mov_b32_e32 v116, 1.0
	s_mov_b32 s67, -4
	s_mov_b32 s68, 64
	v_add_u32_e32 v112, v7, v8
	v_add_u32_e32 v113, v3, v9
	v_add_u32_e32 v114, v1, v9
	v_add_u32_e32 v115, v6, v2
	s_waitcnt vmcnt(8)
	v_mov_b32_e32 v130, v117
	v_mov_b32_e32 v131, v117
	v_mov_b32_e32 v132, v117
	v_mov_b32_e32 v126, v117
	v_mov_b32_e32 v127, v117
	v_mov_b32_e32 v128, v117
	v_mov_b32_e32 v129, v117
	v_mov_b32_e32 v123, 1.0
	v_mov_b32_e32 v124, 1.0
	v_mov_b32_e32 v122, 1.0
	v_mov_b32_e32 v121, 1.0
	v_mov_b32_e32 v120, 1.0
	v_mov_b32_e32 v118, 1.0
	v_mov_b32_e32 v119, 1.0
	v_mov_b32_e32 v1, v0
	v_mov_b32_e32 v2, v0
	v_mov_b32_e32 v3, v0
	v_mov_b32_e32 v4, v0
	v_mov_b32_e32 v5, v0
	v_mov_b32_e32 v6, v0
	v_mov_b32_e32 v7, v0
	v_mov_b32_e32 v8, v0
	v_mov_b32_e32 v9, v0
	v_mov_b32_e32 v10, v0
	v_mov_b32_e32 v11, v0
	v_mov_b32_e32 v12, v0
	v_mov_b32_e32 v13, v0
	v_mov_b32_e32 v14, v0
	v_mov_b32_e32 v15, v0
	v_mov_b32_e32 v24, v0
	v_mov_b32_e32 v25, v0
	v_mov_b32_e32 v26, v0
	v_mov_b32_e32 v27, v0
	v_mov_b32_e32 v16, v0
	v_mov_b32_e32 v17, v0
	v_mov_b32_e32 v18, v0
	v_mov_b32_e32 v19, v0
	v_mov_b32_e32 v20, v0
	v_mov_b32_e32 v21, v0
	v_mov_b32_e32 v22, v0
	v_mov_b32_e32 v23, v0
	v_mov_b32_e32 v28, v0
	v_mov_b32_e32 v29, v0
	v_mov_b32_e32 v30, v0
	v_mov_b32_e32 v31, v0
	v_readlane_b32 s1, v251, 49
	v_readlane_b32 s2, v251, 50
	v_readlane_b32 s3, v251, 51
	v_readlane_b32 s4, v251, 52
	v_readlane_b32 s5, v251, 53
	v_readlane_b32 s6, v251, 54
	v_readlane_b32 s7, v251, 55
	v_readlane_b32 s10, v251, 58
	v_readlane_b32 s11, v251, 59
	v_readlane_b32 s12, v251, 60
	v_readlane_b32 s13, v251, 61
	v_readlane_b32 s14, v251, 62
	v_readlane_b32 s15, v251, 63
	v_bfe_u32 v109, v189, 4, 2
	v_lshlrev_b32_e32 v109, 3, v109
	v_bfe_u32 v110, v189, 2, 2
	v_add_u32_e32 v109, v109, v110
	v_mul_u32_u24_e32 v109, 0x90, v109
	v_and_b32_e32 v110, 3, v189
	v_lshl_add_u32 v109, v110, 3, v109
.LBB0_525:
	s_add_i32 s44, s67, 5
	s_cmp_ge_i32 s44, s64
	s_barrier
	s_waitcnt vmcnt(0)
	ds_write_b128 v112, v[56:59]
	ds_write_b128 v112, v[60:63] offset:4608
	ds_write_b128 v112, v[48:51] offset:9216
	ds_write_b128 v112, v[52:55] offset:13824
	s_waitcnt lgkmcnt(0)
	s_barrier
	s_cbranch_scc1 .LBB0_527
	s_cmp_lt_i32 s44, s59
	s_cselect_b64 s[44:45], -1, 0
	s_and_b64 s[44:45], s[44:45], exec
	s_cselect_b32 s44, 0, s59
	s_cselect_b32 s45, s66, s57
	s_cselect_b32 s46, s65, s56
	s_lshl_b32 s44, s44, 6
	s_sub_i32 s44, s68, s44
	s_add_u32 s44, s44, s46
	s_addc_u32 s45, 0, s45
	v_lshl_add_u64 v[48:49], s[44:45], 0, v[100:101]
	v_lshlrev_b64 v[48:49], 11, v[48:49]
	v_lshl_add_u64 v[52:53], v[102:103], 0, v[48:49]
	global_load_dwordx4 v[56:59], v[52:53], off offset:768
	global_load_dwordx4 v[48:51], v[52:53], off offset:1024
	v_add_co_u32_e32 v52, vcc, 0x10000, v52
	s_nop 1
	v_addc_co_u32_e32 v53, vcc, 0, v53, vcc
	global_load_dwordx4 v[60:63], v[52:53], off offset:768
	s_nop 0
	global_load_dwordx4 v[52:55], v[52:53], off offset:1024

; __device__ __forceinline__ bf16_t f2bf(float f) { return (bf16_t)(pack2(f, 0.f) & 0xffffu); }
; #define MFMA(a, b, c) __builtin_amdgcn_mfma_f32_16x16x32_bf16(a, b, c, 0, 0, 0)
; __device__ __forceinline__ void attn_tile(const Params& p, int l, int tile, unsigned char* smem) {
;     ...
;         float mx = fmaxf(fmaxf(sv0, sv1), fmaxf(sv2, sv3));
;         mx = max16(mx);
;         const float mn = fmaxf(m[mt][j], mx);
;         const float alpha = __expf(m[mt][j] - mn);
;         const float p0 = __expf(sv0 - mn), p1 = __expf(sv1 - mn), p2 = __expf(sv2 - mn), p3 = __expf(sv3 - mn);
;         bf16_t* pr = Ps + (mt * 16 + fq * 4 + j) * 72 + fr;
;         pr[0] = f2bf(p0); pr[16] = f2bf(p1); pr[32] = f2bf(p2); pr[48] = f2bf(p3);
;         const float rsum = sum16(p0 + p1 + p2 + p3);
;         ls[mt][j] = ls[mt][j] * alpha + rsum;
;         m[mt][j] = mn;
; #pragma unroll
;         for (int nt = 0; nt < 4; ++nt) o[mt][nt][j] *= alpha;
;       }
;     }
;     __builtin_amdgcn_wave_barrier();
; #pragma unroll
;     for (int ks = 0; ks < 2; ++ks) {
;       bf16x8 pa[2];
; #pragma unroll
;       for (int mt = 0; mt < 2; ++mt) pa[mt] = *(const bf16x8*)(Ps + (mt * 16 + fr) * 72 + ks * 32 + fq * 8);
; #pragma unroll
;       for (int nt = 0; nt < 4; ++nt) {
;         bf16x8 vb = *(const bf16x8*)(Vt + (nt * 16 + fr) * 72 + ks * 32 + fq * 8);
; #pragma unroll
;         for (int mt = 0; mt < 2; ++mt) o[mt][nt] = MFMA(pa[mt], vb, o[mt][nt]);
;       }
;     }
.LBB0_543:
	v_sub_f32_e32 v74, v131, v72
	v_mul_f32_e32 v74, 0x3fb8aa3b, v74
	v_exp_f32_e32 v77, v74
	v_sub_f32_e32 v74, v130, v73
	v_mul_f32_e32 v74, 0x3fb8aa3b, v74
	v_exp_f32_e32 v78, v74
	v_max_f32_e32 v74, v75, v79
	v_max3_f32 v74, v67, v71, v74
	v_add_f32_e32 v64, v64, v66
	v_sub_f32_e32 v66, v129, v125
	v_max_f32_dpp v74, v74, v74 quad_perm:[1,0,3,2] row_mask:0xf bank_mask:0xf bound_ctrl:1
	v_mul_f32_e32 v66, 0x3fb8aa3b, v66
	v_exp_f32_e32 v142, v66
	v_max_f32_dpp v74, v74, v74 quad_perm:[2,3,0,1] row_mask:0xf bank_mask:0xf bound_ctrl:1
	v_sub_f32_e32 v66, v128, v80
	v_mul_f32_e32 v66, 0x3fb8aa3b, v66
	v_max_f32_dpp v74, v74, v74 row_half_mirror row_mask:0xf bank_mask:0xf bound_ctrl:1
	v_exp_f32_e32 v143, v66
	v_sub_f32_e32 v66, v127, v81
	v_mov_b32_dpp v92, v74 row_mirror row_mask:0xf bank_mask:0xf bound_ctrl:1
	v_max3_f32 v74, v117, v74, v92
	v_sub_f32_e32 v67, v67, v74
	v_mul_f32_e32 v67, 0x3fb8aa3b, v67
	v_exp_f32_e32 v145, v67
	v_sub_f32_e32 v67, v71, v74
	v_mul_f32_e32 v67, 0x3fb8aa3b, v67
	v_exp_f32_e32 v146, v67
	v_sub_f32_e32 v67, v75, v74
	v_mul_f32_e32 v67, 0x3fb8aa3b, v67
	v_exp_f32_e32 v75, v67
	v_sub_f32_e32 v67, v79, v74
	v_mul_f32_e32 v67, 0x3fb8aa3b, v67
	v_exp_f32_e32 v147, v67
	v_cvt_pk_bf16_f32 v67, v145, s0
	ds_write_b16 v115, v67 offset:21168
	v_cvt_pk_bf16_f32 v67, v146, s0
	ds_write_b16 v115, v67 offset:21200
	v_cvt_pk_bf16_f32 v67, v75, s0
	v_mul_f32_e32 v66, 0x3fb8aa3b, v66
	ds_write_b16 v115, v67 offset:21232
	v_cvt_pk_bf16_f32 v67, v147, s0
	v_exp_f32_e32 v144, v66
	v_sub_f32_e32 v66, v126, v82
	ds_write_b16 v115, v67 offset:21264
	ds_read_b128 v[92:95], v113 offset:18432
	v_mul_f32_e32 v66, 0x3fb8aa3b, v66
	v_sub_f32_e32 v70, v132, v83
	v_exp_f32_e32 v71, v66
	v_sub_f32_e32 v66, v117, v74
	v_mul_f32_e32 v70, 0x3fb8aa3b, v70
	v_mul_f32_e32 v66, 0x3fb8aa3b, v66
	v_exp_f32_e32 v70, v70
	ds_read_b128 v[126:129], v113 offset:20736
	ds_read_b64_tr_b16 v[130:131], v109 offset:9216
	ds_read_b64_tr_b16 v[132:133], v109 offset:9792
	v_exp_f32_e32 v117, v66
	v_mul_f32_e32 v13, v13, v77
	v_mul_f32_e32 v12, v12, v70
	v_mul_f32_e32 v14, v14, v78
	v_mul_f32_e32 v28, v28, v142
	v_mul_f32_e32 v29, v29, v143
	v_mul_f32_e32 v30, v30, v144
	v_mul_f32_e32 v31, v31, v71
	v_mul_f32_e32 v15, v15, v117
	ds_read_b64_tr_b16 v[134:135], v109 offset:9248
	ds_read_b64_tr_b16 v[136:137], v109 offset:9824
	s_waitcnt lgkmcnt(2)
	v_mfma_f32_16x16x32_bf16 v[28:31], v[92:95], v[130:133], v[28:31]
	v_mul_f32_e32 v8, v8, v70
	v_mul_f32_e32 v4, v4, v70
	v_mul_f32_e32 v9, v9, v77
	v_mfma_f32_16x16x32_bf16 v[12:15], v[126:129], v[130:133], v[12:15]
	ds_read_b64_tr_b16 v[130:131], v109 offset:9280
	ds_read_b64_tr_b16 v[132:133], v109 offset:9856
	v_mul_f32_e32 v5, v5, v77
	v_mul_f32_e32 v10, v10, v78
	v_mul_f32_e32 v6, v6, v78
	v_mul_f32_e32 v20, v20, v142
	v_mul_f32_e32 v16, v16, v142
	v_mul_f32_e32 v21, v21, v143
	v_mul_f32_e32 v22, v22, v144
	v_mul_f32_e32 v23, v23, v71
	v_mul_f32_e32 v11, v11, v117
	v_mul_f32_e32 v17, v17, v143
	v_mul_f32_e32 v18, v18, v144
	v_mul_f32_e32 v19, v19, v71
	v_mul_f32_e32 v7, v7, v117
	v_mul_f32_e32 v24, v24, v142
	s_waitcnt lgkmcnt(0)
	v_mfma_f32_16x16x32_bf16 v[16:19], v[92:95], v[130:133], v[16:19]
	v_mul_f32_e32 v25, v25, v143
	v_mul_f32_e32 v26, v26, v144
	v_mul_f32_e32 v27, v27, v71
	v_mfma_f32_16x16x32_bf16 v[4:7], v[126:129], v[130:133], v[4:7]
	ds_read_b128 v[130:133], v113 offset:18496
	v_add_f32_e32 v66, v65, v69
	v_mul_f32_e32 v1, v1, v77
	v_mfma_f32_16x16x32_bf16 v[20:23], v[92:95], v[134:137], v[20:23]
	v_mul_f32_e32 v2, v2, v78
	v_fmac_f32_e32 v64, v123, v78
	v_fmac_f32_e32 v66, v124, v77
	v_mfma_f32_16x16x32_bf16 v[8:11], v[126:129], v[134:137], v[8:11]
	ds_read_b64_tr_b16 v[134:135], v109 offset:9312
	ds_read_b64_tr_b16 v[136:137], v109 offset:9888
	v_add_f32_e32 v67, v68, v76
	v_add_f32_e32 v68, v87, v91
	s_waitcnt lgkmcnt(0)
	v_mfma_f32_16x16x32_bf16 v[24:27], v[92:95], v[134:137], v[24:27]
	ds_read_b128 v[92:95], v113 offset:20800
	ds_read_b64_tr_b16 v[138:139], v109 offset:13824
	ds_read_b64_tr_b16 v[140:141], v109 offset:14400
	ds_read_b64_tr_b16 v[76:77], v109 offset:13856
	ds_read_b64_tr_b16 v[78:79], v109 offset:14432
	v_add_f32_e32 v69, v86, v90
	v_mul_f32_e32 v0, v0, v70
	v_mul_f32_e32 v3, v3, v117
	v_fmac_f32_e32 v67, v122, v70
	v_fmac_f32_e32 v68, v121, v71
	v_fmac_f32_e32 v69, v120, v144
	ds_read_b64_tr_b16 v[120:121], v109 offset:13888
	ds_read_b64_tr_b16 v[122:123], v109 offset:14464
	s_waitcnt lgkmcnt(2)
	v_mfma_f32_16x16x32_bf16 v[20:23], v[130:133], v[76:79], v[20:23]
	v_add_f32_e32 v65, v145, v146
	v_add_f32_e32 v65, v75, v65
	v_add_f32_e32 v65, v147, v65
	v_mfma_f32_16x16x32_bf16 v[8:11], v[92:95], v[76:79], v[8:11]
	ds_read_b64_tr_b16 v[76:77], v109 offset:13920
	ds_read_b64_tr_b16 v[78:79], v109 offset:14496
	v_add_f32_dpp v65, v65, v65 quad_perm:[1,0,3,2] row_mask:0xf bank_mask:0xf bound_ctrl:1
	v_add_f32_e32 v70, v85, v89
	v_mfma_f32_16x16x32_bf16 v[0:3], v[126:129], v[134:137], v[0:3]
	v_add_f32_dpp v65, v65, v65 quad_perm:[2,3,0,1] row_mask:0xf bank_mask:0xf bound_ctrl:1
	v_add_f32_e32 v71, v84, v88
	s_add_i32 s67, s67, 1
	v_mfma_f32_16x16x32_bf16 v[28:31], v[130:133], v[138:141], v[28:31]
	v_add_f32_dpp v65, v65, v65 row_half_mirror row_mask:0xf bank_mask:0xf bound_ctrl:1
	s_add_i32 s68, s68, 64
	v_fmac_f32_e32 v70, v118, v143
	v_mfma_f32_16x16x32_bf16 v[12:15], v[92:95], v[138:141], v[12:15]
	v_add_f32_dpp v65, v65, v65 row_mirror row_mask:0xf bank_mask:0xf bound_ctrl:1
	v_fmac_f32_e32 v71, v119, v142
	v_fmac_f32_e32 v65, v116, v117
	s_waitcnt lgkmcnt(2)
	v_mfma_f32_16x16x32_bf16 v[16:19], v[130:133], v[120:123], v[16:19]
	s_cmp_lg_u32 s59, s67
	v_subrev_u32_e32 v111, 64, v111
	v_mfma_f32_16x16x32_bf16 v[4:7], v[92:95], v[120:123], v[4:7]
	s_waitcnt lgkmcnt(0)
	v_mfma_f32_16x16x32_bf16 v[24:27], v[130:133], v[76:79], v[24:27]
	v_mfma_f32_16x16x32_bf16 v[0:3], v[92:95], v[76:79], v[0:3]
	s_cbranch_scc0 .LBB0_505
	v_mov_b32_e32 v117, v74
	v_mov_b32_e32 v130, v73
	v_mov_b32_e32 v131, v72
	v_mov_b32_e32 v132, v83
	v_mov_b32_e32 v126, v82
	v_mov_b32_e32 v127, v81
	v_mov_b32_e32 v128, v80
	v_mov_b32_e32 v129, v125
	v_mov_b32_e32 v116, v65
	v_mov_b32_e32 v123, v64
	v_mov_b32_e32 v124, v66
	v_mov_b32_e32 v122, v67
	v_mov_b32_e32 v121, v68
	v_mov_b32_e32 v120, v69
	v_mov_b32_e32 v118, v70
	v_mov_b32_e32 v119, v71
	s_branch .LBB0_525
